# first norm phase writes the residual copy only for context rows; the first residual epilogue reads latent rows from the input x
# speedup vs baseline: 1.0093x; 1.0072x over previous
;     __device__ __forceinline__ void operator()(const f32x4 (&acc)[2][2][4][2], const Unit& u, int wr, int wc, int fr, int fq) const {
;         const float* gate = MODl + tile_w(u.pm) * NMOD + gate_chunk * 1024;
;         const bool part = u.ko != 0;
;         float* base = part ? PART + ((size_t)((u.ko >> 8) - 1) * 512 + (u.pm == 32 ? 0 : 256) + wr * 64 + fr) * DM : H + (size_t)(u.pm * BM + wr * 64 + fr) * DM;
; #pragma unroll
;         for (int bj = 0; bj < 2; ++bj)
; #pragma unroll
;             for (int n = 0; n < 2; ++n) {
;                 const int col = u.pn * BM + bj * HALF + wc * 32 + n * 16 + fq * 4;
;                 const f32x4 gv = *(const f32x4*)(gate + col) * coef;
;                 f32x4 old[2][4];
; #pragma unroll
;                 for (int ai = 0; ai < 2; ++ai)
; #pragma unroll
;                     for (int m = 0; m < 4; ++m) old[ai][m] = part ? (f32x4){0.f, 0.f, 0.f, 0.f} : *(const f32x4*)(base + (size_t)(ai * HALF + m * 16) * DM + col);
; #pragma unroll
;                 for (int ai = 0; ai < 2; ++ai)
; #pragma unroll
;                     for (int m = 0; m < 4; ++m) *(f32x4*)(base + (size_t)(ai * HALF + m * 16) * DM + col) = old[ai][m] + gv * acc[ai][bj][m][n];
.LBB0_276:
	s_lshr_b32 s8, s53, 31
	s_ashr_i32 s9, s53, 3
	s_add_i32 s8, s9, s8
	s_mul_i32 s9, s8, 0xffffffdf
	s_add_i32 s9, s9, s79
	s_mulk_i32 s8, 0x2400
	s_cmp_lg_u32 s9, 32
	s_cselect_b32 s8, s8, 0x4800
	s_ashr_i32 s9, s8, 31
	s_waitcnt vmcnt(0)
	v_or_b32_e32 v130, s23, v180
	s_lshl_b64 s[8:9], s[8:9], 2
	v_lshl_or_b32 v130, s61, 8, v130
	s_add_u32 s8, s71, s8
	v_ashrrev_i32_e32 v131, 31, v130
	s_addc_u32 s9, s65, s9
	v_lshlrev_b64 v[130:131], 2, v[130:131]
	v_lshl_add_u64 v[210:211], s[8:9], 0, v[130:131]
	v_lshl_add_u64 v[212:213], v[128:129], 0, v[130:131]
	s_and_b64 vcc, exec, s[10:11]
	s_cbranch_vccz .Ler_part
	s_mov_b64 s[8:9], 0
	v_readlane_b32 s12, v254, 30
	s_nop 0
	s_cmp_lg_u32 s12, 3
	s_cbranch_scc1 .Ler_nod
	s_cmp_eq_u32 s79, 32
	s_cbranch_scc1 .Ler_nod
	s_cmp_eq_u32 s79, 0x41
	s_cbranch_scc1 .Ler_nod
	v_readlane_b32 s12, v254, 18
	v_readlane_b32 s13, v254, 19
	s_nop 1
	s_load_dwordx2 s[8:9], s[12:13], 0x0
	s_load_dwordx2 s[12:13], s[12:13], 0xb8
	s_waitcnt lgkmcnt(0)
	s_sub_u32 s8, s8, s12
	s_subb_u32 s9, s9, s13
	s_cmp_gt_u32 s79, 32
	s_cselect_b32 s12, 0x100000, 0
	s_sub_u32 s8, s8, s12
	s_subb_u32 s9, s9, 0
.Ler_nod:
	global_load_dwordx4 v[128:131], v[210:211], off offset:0
	global_load_dwordx4 v[132:135], v[210:211], off offset:64
	global_load_dwordx4 v[136:139], v[210:211], off offset:512
	global_load_dwordx4 v[140:143], v[210:211], off offset:576
	s_mov_b32 s13, 0
	s_mov_b32 s12, 0x10000
	v_lshl_add_u64 v[246:247], v[212:213], 0, s[12:13]
	s_mov_b32 s12, 0x20000
	v_lshl_add_u64 v[248:249], v[212:213], 0, s[12:13]
	s_mov_b32 s12, 0x30000
	v_lshl_add_u64 v[250:251], v[212:213], 0, s[12:13]
	s_mov_b32 s12, 0x80000
	v_lshl_add_u64 v[252:253], v[212:213], 0, s[12:13]
	s_mov_b32 s12, 0x90000
	v_lshl_add_u64 v[218:219], v[212:213], 0, s[12:13]
	s_mov_b32 s12, 0xa0000
	v_lshl_add_u64 v[220:221], v[212:213], 0, s[12:13]
	s_mov_b32 s12, 0xb0000
	v_lshl_add_u64 v[214:215], v[212:213], 0, s[12:13]
	v_lshl_add_u64 v[200:201], v[212:213], 0, s[8:9]
	global_load_dwordx4 v[144:147], v[200:201], off offset:0
	v_lshl_add_u64 v[202:203], v[212:213], 0, s[8:9]
	global_load_dwordx4 v[148:151], v[202:203], off offset:64
	v_lshl_add_u64 v[204:205], v[212:213], 0, s[8:9]
	global_load_dwordx4 v[152:155], v[204:205], off offset:512
	v_lshl_add_u64 v[206:207], v[212:213], 0, s[8:9]
	global_load_dwordx4 v[156:159], v[206:207], off offset:576
	v_lshl_add_u64 v[200:201], v[246:247], 0, s[8:9]
	global_load_dwordx4 v[160:163], v[200:201], off offset:0
	v_lshl_add_u64 v[202:203], v[246:247], 0, s[8:9]
	global_load_dwordx4 v[234:237], v[202:203], off offset:64
	v_lshl_add_u64 v[204:205], v[246:247], 0, s[8:9]
	global_load_dwordx4 v[238:241], v[204:205], off offset:512
	v_lshl_add_u64 v[206:207], v[246:247], 0, s[8:9]
	global_load_dwordx4 v[242:245], v[206:207], off offset:576
	v_mov_b32_e32 v171, v170
	s_waitcnt vmcnt(8)
	v_pk_mul_f32 v[130:131], v[170:171], v[130:131]
	v_pk_mul_f32 v[128:129], v[172:173], v[128:129]
	v_pk_mul_f32 v[134:135], v[170:171], v[134:135]
	v_pk_mul_f32 v[132:133], v[172:173], v[132:133]
	v_pk_mul_f32 v[138:139], v[170:171], v[138:139]
	v_pk_mul_f32 v[136:137], v[172:173], v[136:137]
	v_pk_mul_f32 v[142:143], v[170:171], v[142:143]
	v_pk_mul_f32 v[140:141], v[172:173], v[140:141]
	s_waitcnt vmcnt(7)
	v_pk_fma_f32 v[146:147], v[126:127], v[130:131], v[146:147]
	v_pk_fma_f32 v[144:145], v[124:125], v[128:129], v[144:145]
	global_store_dwordx4 v[212:213], v[144:147], off offset:0
	s_nop 0
	v_lshl_add_u64 v[200:201], v[248:249], 0, s[8:9]
	global_load_dwordx4 v[144:147], v[200:201], off offset:0
	s_waitcnt vmcnt(8)
	v_pk_fma_f32 v[150:151], v[118:119], v[134:135], v[150:151]
	v_pk_fma_f32 v[148:149], v[116:117], v[132:133], v[148:149]
	global_store_dwordx4 v[212:213], v[148:151], off offset:64
	s_nop 0
	v_lshl_add_u64 v[202:203], v[248:249], 0, s[8:9]
	global_load_dwordx4 v[148:151], v[202:203], off offset:64
	s_waitcnt vmcnt(9)
	v_pk_fma_f32 v[154:155], v[122:123], v[138:139], v[154:155]
	v_pk_fma_f32 v[152:153], v[120:121], v[136:137], v[152:153]
	global_store_dwordx4 v[212:213], v[152:155], off offset:512
	s_nop 0
	v_lshl_add_u64 v[204:205], v[248:249], 0, s[8:9]
	global_load_dwordx4 v[152:155], v[204:205], off offset:512
	s_waitcnt vmcnt(10)
	v_pk_fma_f32 v[158:159], v[114:115], v[142:143], v[158:159]
	v_pk_fma_f32 v[156:157], v[112:113], v[140:141], v[156:157]
	global_store_dwordx4 v[212:213], v[156:159], off offset:576
	s_nop 0
	v_lshl_add_u64 v[206:207], v[248:249], 0, s[8:9]
	global_load_dwordx4 v[156:159], v[206:207], off offset:576
	s_waitcnt vmcnt(11)
	v_pk_fma_f32 v[162:163], v[110:111], v[130:131], v[162:163]
	v_pk_fma_f32 v[160:161], v[108:109], v[128:129], v[160:161]
	global_store_dwordx4 v[246:247], v[160:163], off offset:0
	s_nop 0
	v_lshl_add_u64 v[200:201], v[250:251], 0, s[8:9]
	global_load_dwordx4 v[160:163], v[200:201], off offset:0
	s_waitcnt vmcnt(12)
	v_pk_fma_f32 v[236:237], v[102:103], v[134:135], v[236:237]
	v_pk_fma_f32 v[234:235], v[100:101], v[132:133], v[234:235]
	global_store_dwordx4 v[246:247], v[234:237], off offset:64
	s_nop 0
	v_lshl_add_u64 v[202:203], v[250:251], 0, s[8:9]
	global_load_dwordx4 v[234:237], v[202:203], off offset:64
	s_waitcnt vmcnt(13)
	v_pk_fma_f32 v[240:241], v[106:107], v[138:139], v[240:241]
	v_pk_fma_f32 v[238:239], v[104:105], v[136:137], v[238:239]
	global_store_dwordx4 v[246:247], v[238:241], off offset:512
	s_nop 0
	v_lshl_add_u64 v[204:205], v[250:251], 0, s[8:9]
	global_load_dwordx4 v[238:241], v[204:205], off offset:512
	s_waitcnt vmcnt(14)
;     __device__ __forceinline__ void operator()(const f32x4 (&acc)[2][2][4][2], const Unit& u, int wr, int wc, int fr, int fq) const {
;     ...
;             for (int n = 0; n < 2; ++n) {
;                 const int col = u.pn * BM + bj * HALF + wc * 32 + n * 16 + fq * 4;
;                 const f32x4 gv = *(const f32x4*)(gate + col) * coef;
;                 f32x4 old[2][4];
; #pragma unroll
;                 for (int ai = 0; ai < 2; ++ai)
; #pragma unroll
;                     for (int m = 0; m < 4; ++m) old[ai][m] = part ? (f32x4){0.f, 0.f, 0.f, 0.f} : *(const f32x4*)(base + (size_t)(ai * HALF + m * 16) * DM + col);
; #pragma unroll
;                 for (int ai = 0; ai < 2; ++ai)
; #pragma unroll
;                     for (int m = 0; m < 4; ++m) *(f32x4*)(base + (size_t)(ai * HALF + m * 16) * DM + col) = old[ai][m] + gv * acc[ai][bj][m][n];
	v_pk_fma_f32 v[244:245], v[98:99], v[142:143], v[244:245]
	v_pk_fma_f32 v[242:243], v[96:97], v[140:141], v[242:243]
	global_store_dwordx4 v[246:247], v[242:245], off offset:576
	s_nop 0
	v_lshl_add_u64 v[206:207], v[250:251], 0, s[8:9]
	global_load_dwordx4 v[242:245], v[206:207], off offset:576
	s_waitcnt vmcnt(14)
	v_pk_fma_f32 v[146:147], v[94:95], v[130:131], v[146:147]
	v_pk_fma_f32 v[144:145], v[92:93], v[128:129], v[144:145]
	global_store_dwordx4 v[248:249], v[144:147], off offset:0
	s_nop 0
	v_lshl_add_u64 v[200:201], v[252:253], 0, s[8:9]
	global_load_dwordx4 v[144:147], v[200:201], off offset:0
	s_waitcnt vmcnt(14)
	v_pk_fma_f32 v[150:151], v[86:87], v[134:135], v[150:151]
	v_pk_fma_f32 v[148:149], v[84:85], v[132:133], v[148:149]
	global_store_dwordx4 v[248:249], v[148:151], off offset:64
	s_nop 0
	v_lshl_add_u64 v[202:203], v[252:253], 0, s[8:9]
	global_load_dwordx4 v[148:151], v[202:203], off offset:64
	s_waitcnt vmcnt(14)
	v_pk_fma_f32 v[154:155], v[90:91], v[138:139], v[154:155]
	v_pk_fma_f32 v[152:153], v[88:89], v[136:137], v[152:153]
	global_store_dwordx4 v[248:249], v[152:155], off offset:512
	s_nop 0
	v_lshl_add_u64 v[204:205], v[252:253], 0, s[8:9]
	global_load_dwordx4 v[152:155], v[204:205], off offset:512
	s_waitcnt vmcnt(14)
	v_pk_fma_f32 v[158:159], v[82:83], v[142:143], v[158:159]
	v_pk_fma_f32 v[156:157], v[80:81], v[140:141], v[156:157]
	global_store_dwordx4 v[248:249], v[156:159], off offset:576
	s_nop 0
	v_lshl_add_u64 v[206:207], v[252:253], 0, s[8:9]
	global_load_dwordx4 v[156:159], v[206:207], off offset:576
	s_waitcnt vmcnt(14)
	v_pk_fma_f32 v[162:163], v[78:79], v[130:131], v[162:163]
	v_pk_fma_f32 v[160:161], v[76:77], v[128:129], v[160:161]
	global_store_dwordx4 v[250:251], v[160:163], off offset:0
	s_nop 0
	v_lshl_add_u64 v[200:201], v[218:219], 0, s[8:9]
	global_load_dwordx4 v[160:163], v[200:201], off offset:0
	s_waitcnt vmcnt(14)
	v_pk_fma_f32 v[236:237], v[70:71], v[134:135], v[236:237]
	v_pk_fma_f32 v[234:235], v[68:69], v[132:133], v[234:235]
	global_store_dwordx4 v[250:251], v[234:237], off offset:64
	s_nop 0
	v_lshl_add_u64 v[202:203], v[218:219], 0, s[8:9]
	global_load_dwordx4 v[234:237], v[202:203], off offset:64
	s_waitcnt vmcnt(14)
	v_pk_fma_f32 v[240:241], v[74:75], v[138:139], v[240:241]
	v_pk_fma_f32 v[238:239], v[72:73], v[136:137], v[238:239]
	global_store_dwordx4 v[250:251], v[238:241], off offset:512
	s_nop 0
	v_lshl_add_u64 v[204:205], v[218:219], 0, s[8:9]
	global_load_dwordx4 v[238:241], v[204:205], off offset:512
	s_waitcnt vmcnt(14)
	v_pk_fma_f32 v[244:245], v[66:67], v[142:143], v[244:245]
	v_pk_fma_f32 v[242:243], v[64:65], v[140:141], v[242:243]
	global_store_dwordx4 v[250:251], v[242:245], off offset:576
	s_nop 0
	v_lshl_add_u64 v[206:207], v[218:219], 0, s[8:9]
	global_load_dwordx4 v[242:245], v[206:207], off offset:576
	s_waitcnt vmcnt(14)
	v_pk_fma_f32 v[146:147], v[62:63], v[130:131], v[146:147]
	v_pk_fma_f32 v[144:145], v[60:61], v[128:129], v[144:145]
	global_store_dwordx4 v[252:253], v[144:147], off offset:0
	s_nop 0
	v_lshl_add_u64 v[200:201], v[220:221], 0, s[8:9]
	global_load_dwordx4 v[144:147], v[200:201], off offset:0
	s_waitcnt vmcnt(14)
	v_pk_fma_f32 v[150:151], v[54:55], v[134:135], v[150:151]
	v_pk_fma_f32 v[148:149], v[52:53], v[132:133], v[148:149]
	global_store_dwordx4 v[252:253], v[148:151], off offset:64
	s_nop 0
	v_lshl_add_u64 v[202:203], v[220:221], 0, s[8:9]
	global_load_dwordx4 v[148:151], v[202:203], off offset:64
	s_waitcnt vmcnt(14)
	v_pk_fma_f32 v[154:155], v[58:59], v[138:139], v[154:155]
	v_pk_fma_f32 v[152:153], v[56:57], v[136:137], v[152:153]
	global_store_dwordx4 v[252:253], v[152:155], off offset:512
	s_nop 0
	v_lshl_add_u64 v[204:205], v[220:221], 0, s[8:9]
	global_load_dwordx4 v[152:155], v[204:205], off offset:512
	s_waitcnt vmcnt(14)
	v_pk_fma_f32 v[158:159], v[50:51], v[142:143], v[158:159]
	v_pk_fma_f32 v[156:157], v[48:49], v[140:141], v[156:157]
	global_store_dwordx4 v[252:253], v[156:159], off offset:576
	s_nop 0
	v_lshl_add_u64 v[206:207], v[220:221], 0, s[8:9]
	global_load_dwordx4 v[156:159], v[206:207], off offset:576
	s_waitcnt vmcnt(14)
	v_pk_fma_f32 v[162:163], v[46:47], v[130:131], v[162:163]
	v_pk_fma_f32 v[160:161], v[44:45], v[128:129], v[160:161]
	global_store_dwordx4 v[218:219], v[160:163], off offset:0
	s_nop 0
	v_lshl_add_u64 v[200:201], v[214:215], 0, s[8:9]
	global_load_dwordx4 v[160:163], v[200:201], off offset:0
	s_waitcnt vmcnt(14)
	v_pk_fma_f32 v[236:237], v[38:39], v[134:135], v[236:237]
	v_pk_fma_f32 v[234:235], v[36:37], v[132:133], v[234:235]
	global_store_dwordx4 v[218:219], v[234:237], off offset:64
	s_nop 0
	v_lshl_add_u64 v[202:203], v[214:215], 0, s[8:9]
	global_load_dwordx4 v[234:237], v[202:203], off offset:64
	s_waitcnt vmcnt(14)
	v_pk_fma_f32 v[240:241], v[42:43], v[138:139], v[240:241]
	v_pk_fma_f32 v[238:239], v[40:41], v[136:137], v[238:239]
	global_store_dwordx4 v[218:219], v[238:241], off offset:512
	s_nop 0
	v_lshl_add_u64 v[204:205], v[214:215], 0, s[8:9]
	global_load_dwordx4 v[238:241], v[204:205], off offset:512
	s_waitcnt vmcnt(14)
	v_pk_fma_f32 v[244:245], v[34:35], v[142:143], v[244:245]
	v_pk_fma_f32 v[242:243], v[32:33], v[140:141], v[242:243]
	global_store_dwordx4 v[218:219], v[242:245], off offset:576
	s_nop 0
	v_lshl_add_u64 v[206:207], v[214:215], 0, s[8:9]
	global_load_dwordx4 v[242:245], v[206:207], off offset:576
	s_waitcnt vmcnt(14)
	v_pk_fma_f32 v[146:147], v[30:31], v[130:131], v[146:147]
	v_pk_fma_f32 v[144:145], v[28:29], v[128:129], v[144:145]
	global_store_dwordx4 v[220:221], v[144:147], off offset:0
	s_waitcnt vmcnt(13)
	v_pk_fma_f32 v[150:151], v[22:23], v[134:135], v[150:151]
	v_pk_fma_f32 v[148:149], v[20:21], v[132:133], v[148:149]
	global_store_dwordx4 v[220:221], v[148:151], off offset:64
	s_waitcnt vmcnt(12)
	v_pk_fma_f32 v[154:155], v[26:27], v[138:139], v[154:155]
	v_pk_fma_f32 v[152:153], v[24:25], v[136:137], v[152:153]
	global_store_dwordx4 v[220:221], v[152:155], off offset:512
	s_waitcnt vmcnt(11)
	v_pk_fma_f32 v[158:159], v[18:19], v[142:143], v[158:159]
	v_pk_fma_f32 v[156:157], v[16:17], v[140:141], v[156:157]
	global_store_dwordx4 v[220:221], v[156:159], off offset:576
	s_waitcnt vmcnt(10)
	v_pk_fma_f32 v[162:163], v[14:15], v[130:131], v[162:163]
	v_pk_fma_f32 v[160:161], v[12:13], v[128:129], v[160:161]
	global_store_dwordx4 v[214:215], v[160:163], off offset:0
	s_waitcnt vmcnt(9)
	v_pk_fma_f32 v[236:237], v[6:7], v[134:135], v[236:237]
	v_pk_fma_f32 v[234:235], v[4:5], v[132:133], v[234:235]
	global_store_dwordx4 v[214:215], v[234:237], off offset:64
	s_waitcnt vmcnt(8)
	v_pk_fma_f32 v[240:241], v[10:11], v[138:139], v[240:241]
	v_pk_fma_f32 v[238:239], v[8:9], v[136:137], v[238:239]
	global_store_dwordx4 v[214:215], v[238:241], off offset:512
	s_waitcnt vmcnt(7)
	v_pk_fma_f32 v[244:245], v[2:3], v[142:143], v[244:245]
	v_pk_fma_f32 v[242:243], v[0:1], v[140:141], v[242:243]
	global_store_dwordx4 v[214:215], v[242:245], off offset:576
	s_branch .LBB0_341

; __device__ __forceinline__ void norm_phase(KP P, const float* g, const float* MODl, int shc, int scc, bool from_input, int npart) {
;     ...
;                 if (from_input || (t >= SEQ && npart > 0)) {
; #pragma unroll
;                     for (int j = 0; j < 4; ++j) ((float4*)(H + (size_t)row * DM))[lane + 64 * j] = v[u][j]; }
.Lnm_fi0_wdone:
	s_cmp_ge_u32 s0, 0x2100
	s_cselect_b32 s6, 1, 0
	s_mul_i32 s7, s6, 0x2100
	s_sub_u32 s7, s0, s7
	s_cmp_ge_u32 s7, 0x2000
	s_cselect_b32 s30, 2, s6
	s_lshl_b32 s31, s0, 12
	s_add_u32 s64, s60, s31
	s_addc_u32 s65, s61, 0
	s_cmp_lt_u32 s7, 0x2000
	s_cbranch_scc1 .Lnm_fi0_noh
	global_store_dwordx4 v112, v[0:3], s[64:65] offset:0
	global_store_dwordx4 v112, v[4:7], s[64:65] offset:1024
	global_store_dwordx4 v112, v[8:11], s[64:65] offset:2048
	global_store_dwordx4 v112, v[12:15], s[64:65] offset:3072
	s_add_u32 s23, s23, 4

; __device__ __forceinline__ unsigned pk2(float lo, float hi) { return (unsigned)f2bf(lo) | ((unsigned)f2bf(hi) << 16); }
; __device__ __forceinline__ void norm_phase(KP P, const float* g, const float* MODl, int shc, int scc, bool from_input, int npart) {
;     ...
;                 for (int j = 0; j < 4; ++j) ss[u] += v[u][j].x * v[u][j].x + v[u][j].y * v[u][j].y + v[u][j].z * v[u][j].z + v[u][j].w * v[u][j].w;
;                 if (from_input || (t >= SEQ && npart > 0)) {
; #pragma unroll
;                     for (int j = 0; j < 4; ++j) ((float4*)(H + (size_t)row * DM))[lane + 64 * j] = v[u][j]; }
;                 const float r = rsqrtf(wave_sum(ss[u]) * (1.f / DM) + 1e-6f);
;                 const float* sh = MODl + w * NMOD + shc * 1024; const float* sc = MODl + w * NMOD + scc * 1024;
; #pragma unroll
;                 for (int j = 0; j < 4; ++j) { const int c = (lane + 64 * j) * 4; const float4 gg = *(const float4*)(g + c), s4 = *(const float4*)(sh + c), c4 = *(const float4*)(sc + c);
;                     uint2 o; o.x = pk2(v[u][j].x * r * gg.x * (1.f + c4.x) + s4.x, v[u][j].y * r * gg.y * (1.f + c4.y) + s4.y);
;                     o.y = pk2(v[u][j].z * r * gg.z * (1.f + c4.z) + s4.z, v[u][j].w * r * gg.w * (1.f + c4.w) + s4.w);
;                     *(uint2*)(XN + (size_t)row * DM + c) = o; } } }
.Lnm_fi0_tabok:
	v_pk_mul_f32 v[120:121], v[0:1], v[0:1]
	v_add_f32_e32 v125, v121, v120
	v_pk_mul_f32 v[120:121], v[2:3], v[2:3]
	v_add_f32_e32 v125, v120, v125
	v_add_f32_e32 v125, v121, v125
	v_pk_mul_f32 v[120:121], v[4:5], v[4:5]
	v_add_f32_e32 v124, v121, v120
	v_pk_mul_f32 v[120:121], v[6:7], v[6:7]
	v_add_f32_e32 v124, v120, v124
	v_add_f32_e32 v124, v121, v124
	v_add_f32_e32 v125, v124, v125
	v_pk_mul_f32 v[120:121], v[8:9], v[8:9]
	v_add_f32_e32 v124, v121, v120
	v_pk_mul_f32 v[120:121], v[10:11], v[10:11]
	v_add_f32_e32 v124, v120, v124
	v_add_f32_e32 v124, v121, v124
	v_add_f32_e32 v125, v124, v125
	v_pk_mul_f32 v[120:121], v[12:13], v[12:13]
	v_add_f32_e32 v124, v121, v120
	v_pk_mul_f32 v[120:121], v[14:15], v[14:15]
	v_add_f32_e32 v124, v120, v124
	v_add_f32_e32 v124, v121, v124
	v_add_f32_e32 v125, v124, v125
	ds_bpermute_b32 v120, v114, v125
	s_waitcnt lgkmcnt(0)
	v_add_f32_e32 v125, v125, v120
	ds_bpermute_b32 v120, v115, v125
	s_waitcnt lgkmcnt(0)
	v_add_f32_e32 v125, v125, v120
	ds_bpermute_b32 v120, v116, v125
	s_waitcnt lgkmcnt(0)
	v_add_f32_e32 v125, v125, v120
	ds_bpermute_b32 v120, v117, v125
	s_waitcnt lgkmcnt(0)
	v_add_f32_e32 v125, v125, v120
	ds_bpermute_b32 v120, v118, v125
	s_waitcnt lgkmcnt(0)
	v_add_f32_e32 v125, v125, v120
	ds_bpermute_b32 v120, v119, v125
	s_waitcnt lgkmcnt(0)
	v_add_f32_e32 v125, v125, v120
	v_fmamk_f32 v125, v125, 0x3a800000, v217
	v_rsq_f32_e32 v122, v125
	s_lshl_b32 s31, s0, 11
	s_add_u32 s6, s62, s31
	s_addc_u32 s7, s63, 0
	v_pk_mul_f32 v[124:125], v[0:1], v[122:123] op_sel_hi:[1,0]
	v_pk_mul_f32 v[124:125], v[64:65], v[124:125]
	v_pk_fma_f32 v[124:125], v[96:97], v[124:125], v[80:81]
	v_pk_mul_f32 v[120:121], v[2:3], v[122:123] op_sel_hi:[1,0]
	v_pk_mul_f32 v[120:121], v[66:67], v[120:121]
	v_pk_fma_f32 v[120:121], v[98:99], v[120:121], v[82:83]
	v_cvt_pk_bf16_f32 v124, v124, v125
	v_cvt_pk_bf16_f32 v125, v120, v121
	global_store_dwordx2 v113, v[124:125], s[6:7] offset:0
	v_pk_mul_f32 v[124:125], v[4:5], v[122:123] op_sel_hi:[1,0]
	v_pk_mul_f32 v[124:125], v[68:69], v[124:125]
	v_pk_fma_f32 v[124:125], v[100:101], v[124:125], v[84:85]
	v_pk_mul_f32 v[120:121], v[6:7], v[122:123] op_sel_hi:[1,0]
	v_pk_mul_f32 v[120:121], v[70:71], v[120:121]
	v_pk_fma_f32 v[120:121], v[102:103], v[120:121], v[86:87]
	v_cvt_pk_bf16_f32 v124, v124, v125
	v_cvt_pk_bf16_f32 v125, v120, v121
	global_store_dwordx2 v113, v[124:125], s[6:7] offset:512
	v_pk_mul_f32 v[124:125], v[8:9], v[122:123] op_sel_hi:[1,0]
	v_pk_mul_f32 v[124:125], v[72:73], v[124:125]
	v_pk_fma_f32 v[124:125], v[104:105], v[124:125], v[88:89]
	v_pk_mul_f32 v[120:121], v[10:11], v[122:123] op_sel_hi:[1,0]
	v_pk_mul_f32 v[120:121], v[74:75], v[120:121]
	v_pk_fma_f32 v[120:121], v[106:107], v[120:121], v[90:91]
	v_cvt_pk_bf16_f32 v124, v124, v125
	v_cvt_pk_bf16_f32 v125, v120, v121
	global_store_dwordx2 v113, v[124:125], s[6:7] offset:1024
	v_pk_mul_f32 v[124:125], v[12:13], v[122:123] op_sel_hi:[1,0]
	v_pk_mul_f32 v[124:125], v[76:77], v[124:125]
	v_pk_fma_f32 v[124:125], v[108:109], v[124:125], v[92:93]
	v_pk_mul_f32 v[120:121], v[14:15], v[122:123] op_sel_hi:[1,0]
	v_pk_mul_f32 v[120:121], v[78:79], v[120:121]
	v_pk_fma_f32 v[120:121], v[110:111], v[120:121], v[94:95]
	v_cvt_pk_bf16_f32 v124, v124, v125
	v_cvt_pk_bf16_f32 v125, v120, v121
	global_store_dwordx2 v113, v[124:125], s[6:7] offset:1536
	s_add_u32 s23, s23, 4
	s_mul_i32 s31, s2, 4
	s_add_i32 s31, s0, s31
	s_cmp_lt_u32 s31, 0x4200
	s_cbranch_scc0 .Lnm_fi0_nopf
	s_cmp_ge_u32 s31, 0x2100
	s_cselect_b32 s6, 1, 0
	s_mul_i32 s7, s6, 0x2100
	s_sub_u32 s7, s31, s7
	s_cmp_ge_u32 s7, 0x2000
	s_cbranch_scc1 .Lnm_fi4_ctxp
	s_lshl_b32 s6, s6, 13
	s_add_u32 s6, s6, s7
	s_lshl_b32 s6, s6, 12
	s_add_u32 s64, s20, s6
	s_addc_u32 s65, s21, 0
	s_branch .Lnm_fi4_ptrd

; __device__ __forceinline__ void norm_phase(KP P, const float* g, const float* MODl, int shc, int scc, bool from_input, int npart) {
;     ...
;                 if (from_input || (t >= SEQ && npart > 0)) {
; #pragma unroll
;                     for (int j = 0; j < 4; ++j) ((float4*)(H + (size_t)row * DM))[lane + 64 * j] = v[u][j]; }
.Lnm_fi1_wdone:
	s_cmp_ge_u32 s0, 0x2100
	s_cselect_b32 s6, 1, 0
	s_mul_i32 s7, s6, 0x2100
	s_sub_u32 s7, s0, s7
	s_cmp_ge_u32 s7, 0x2000
	s_cselect_b32 s30, 2, s6
	s_lshl_b32 s31, s0, 12
	s_add_u32 s64, s60, s31
	s_addc_u32 s65, s61, 0
	s_cmp_lt_u32 s7, 0x2000
	s_cbranch_scc1 .Lnm_fi1_noh
	global_store_dwordx4 v112, v[16:19], s[64:65] offset:0
	global_store_dwordx4 v112, v[20:23], s[64:65] offset:1024
	global_store_dwordx4 v112, v[24:27], s[64:65] offset:2048
	global_store_dwordx4 v112, v[28:31], s[64:65] offset:3072
	s_add_u32 s23, s23, 4

; __device__ __forceinline__ unsigned pk2(float lo, float hi) { return (unsigned)f2bf(lo) | ((unsigned)f2bf(hi) << 16); }
; __device__ __forceinline__ void norm_phase(KP P, const float* g, const float* MODl, int shc, int scc, bool from_input, int npart) {
;     ...
;                 for (int j = 0; j < 4; ++j) ss[u] += v[u][j].x * v[u][j].x + v[u][j].y * v[u][j].y + v[u][j].z * v[u][j].z + v[u][j].w * v[u][j].w;
;                 if (from_input || (t >= SEQ && npart > 0)) {
; #pragma unroll
;                     for (int j = 0; j < 4; ++j) ((float4*)(H + (size_t)row * DM))[lane + 64 * j] = v[u][j]; }
;                 const float r = rsqrtf(wave_sum(ss[u]) * (1.f / DM) + 1e-6f);
;                 const float* sh = MODl + w * NMOD + shc * 1024; const float* sc = MODl + w * NMOD + scc * 1024;
; #pragma unroll
;                 for (int j = 0; j < 4; ++j) { const int c = (lane + 64 * j) * 4; const float4 gg = *(const float4*)(g + c), s4 = *(const float4*)(sh + c), c4 = *(const float4*)(sc + c);
;                     uint2 o; o.x = pk2(v[u][j].x * r * gg.x * (1.f + c4.x) + s4.x, v[u][j].y * r * gg.y * (1.f + c4.y) + s4.y);
;                     o.y = pk2(v[u][j].z * r * gg.z * (1.f + c4.z) + s4.z, v[u][j].w * r * gg.w * (1.f + c4.w) + s4.w);
;                     *(uint2*)(XN + (size_t)row * DM + c) = o; } } }
.Lnm_fi1_tabok:
	v_pk_mul_f32 v[120:121], v[16:17], v[16:17]
	v_add_f32_e32 v125, v121, v120
	v_pk_mul_f32 v[120:121], v[18:19], v[18:19]
	v_add_f32_e32 v125, v120, v125
	v_add_f32_e32 v125, v121, v125
	v_pk_mul_f32 v[120:121], v[20:21], v[20:21]
	v_add_f32_e32 v124, v121, v120
	v_pk_mul_f32 v[120:121], v[22:23], v[22:23]
	v_add_f32_e32 v124, v120, v124
	v_add_f32_e32 v124, v121, v124
	v_add_f32_e32 v125, v124, v125
	v_pk_mul_f32 v[120:121], v[24:25], v[24:25]
	v_add_f32_e32 v124, v121, v120
	v_pk_mul_f32 v[120:121], v[26:27], v[26:27]
	v_add_f32_e32 v124, v120, v124
	v_add_f32_e32 v124, v121, v124
	v_add_f32_e32 v125, v124, v125
	v_pk_mul_f32 v[120:121], v[28:29], v[28:29]
	v_add_f32_e32 v124, v121, v120
	v_pk_mul_f32 v[120:121], v[30:31], v[30:31]
	v_add_f32_e32 v124, v120, v124
	v_add_f32_e32 v124, v121, v124
	v_add_f32_e32 v125, v124, v125
	ds_bpermute_b32 v120, v114, v125
	s_waitcnt lgkmcnt(0)
	v_add_f32_e32 v125, v125, v120
	ds_bpermute_b32 v120, v115, v125
	s_waitcnt lgkmcnt(0)
	v_add_f32_e32 v125, v125, v120
	ds_bpermute_b32 v120, v116, v125
	s_waitcnt lgkmcnt(0)
	v_add_f32_e32 v125, v125, v120
	ds_bpermute_b32 v120, v117, v125
	s_waitcnt lgkmcnt(0)
	v_add_f32_e32 v125, v125, v120
	ds_bpermute_b32 v120, v118, v125
	s_waitcnt lgkmcnt(0)
	v_add_f32_e32 v125, v125, v120
	ds_bpermute_b32 v120, v119, v125
	s_waitcnt lgkmcnt(0)
	v_add_f32_e32 v125, v125, v120
	v_fmamk_f32 v125, v125, 0x3a800000, v217
	v_rsq_f32_e32 v122, v125
	s_lshl_b32 s31, s0, 11
	s_add_u32 s6, s62, s31
	s_addc_u32 s7, s63, 0
	v_pk_mul_f32 v[124:125], v[16:17], v[122:123] op_sel_hi:[1,0]
	v_pk_mul_f32 v[124:125], v[64:65], v[124:125]
	v_pk_fma_f32 v[124:125], v[96:97], v[124:125], v[80:81]
	v_pk_mul_f32 v[120:121], v[18:19], v[122:123] op_sel_hi:[1,0]
	v_pk_mul_f32 v[120:121], v[66:67], v[120:121]
	v_pk_fma_f32 v[120:121], v[98:99], v[120:121], v[82:83]
	v_cvt_pk_bf16_f32 v124, v124, v125
	v_cvt_pk_bf16_f32 v125, v120, v121
	global_store_dwordx2 v113, v[124:125], s[6:7] offset:0
	v_pk_mul_f32 v[124:125], v[20:21], v[122:123] op_sel_hi:[1,0]
	v_pk_mul_f32 v[124:125], v[68:69], v[124:125]
	v_pk_fma_f32 v[124:125], v[100:101], v[124:125], v[84:85]
	v_pk_mul_f32 v[120:121], v[22:23], v[122:123] op_sel_hi:[1,0]
	v_pk_mul_f32 v[120:121], v[70:71], v[120:121]
	v_pk_fma_f32 v[120:121], v[102:103], v[120:121], v[86:87]
	v_cvt_pk_bf16_f32 v124, v124, v125
	v_cvt_pk_bf16_f32 v125, v120, v121
	global_store_dwordx2 v113, v[124:125], s[6:7] offset:512
	v_pk_mul_f32 v[124:125], v[24:25], v[122:123] op_sel_hi:[1,0]
	v_pk_mul_f32 v[124:125], v[72:73], v[124:125]
	v_pk_fma_f32 v[124:125], v[104:105], v[124:125], v[88:89]
	v_pk_mul_f32 v[120:121], v[26:27], v[122:123] op_sel_hi:[1,0]
	v_pk_mul_f32 v[120:121], v[74:75], v[120:121]
	v_pk_fma_f32 v[120:121], v[106:107], v[120:121], v[90:91]
	v_cvt_pk_bf16_f32 v124, v124, v125
	v_cvt_pk_bf16_f32 v125, v120, v121
	global_store_dwordx2 v113, v[124:125], s[6:7] offset:1024
	v_pk_mul_f32 v[124:125], v[28:29], v[122:123] op_sel_hi:[1,0]
	v_pk_mul_f32 v[124:125], v[76:77], v[124:125]
	v_pk_fma_f32 v[124:125], v[108:109], v[124:125], v[92:93]
	v_pk_mul_f32 v[120:121], v[30:31], v[122:123] op_sel_hi:[1,0]
	v_pk_mul_f32 v[120:121], v[78:79], v[120:121]
	v_pk_fma_f32 v[120:121], v[110:111], v[120:121], v[94:95]
	v_cvt_pk_bf16_f32 v124, v124, v125
	v_cvt_pk_bf16_f32 v125, v120, v121
	global_store_dwordx2 v113, v[124:125], s[6:7] offset:1536
	s_add_u32 s23, s23, 4
	s_mul_i32 s31, s2, 4
	s_add_i32 s31, s0, s31
	s_cmp_lt_u32 s31, 0x4200
	s_cbranch_scc0 .Lnm_fi1_nopf
	s_cmp_ge_u32 s31, 0x2100
	s_cselect_b32 s6, 1, 0
	s_mul_i32 s7, s6, 0x2100
	s_sub_u32 s7, s31, s7
	s_cmp_ge_u32 s7, 0x2000
	s_cbranch_scc1 .Lnm_fi5_ctxp
	s_lshl_b32 s6, s6, 13
	s_add_u32 s6, s6, s7
	s_lshl_b32 s6, s6, 12
	s_add_u32 s64, s20, s6
	s_addc_u32 s65, s21, 0
	s_branch .Lnm_fi5_ptrd

; __device__ __forceinline__ void norm_phase(KP P, const float* g, const float* MODl, int shc, int scc, bool from_input, int npart) {
;     ...
;                 if (from_input || (t >= SEQ && npart > 0)) {
; #pragma unroll
;                     for (int j = 0; j < 4; ++j) ((float4*)(H + (size_t)row * DM))[lane + 64 * j] = v[u][j]; }
.Lnm_fi2_wdone:
	s_cmp_ge_u32 s0, 0x2100
	s_cselect_b32 s6, 1, 0
	s_mul_i32 s7, s6, 0x2100
	s_sub_u32 s7, s0, s7
	s_cmp_ge_u32 s7, 0x2000
	s_cselect_b32 s30, 2, s6
	s_lshl_b32 s31, s0, 12
	s_add_u32 s64, s60, s31
	s_addc_u32 s65, s61, 0
	s_cmp_lt_u32 s7, 0x2000
	s_cbranch_scc1 .Lnm_fi2_noh
	global_store_dwordx4 v112, v[32:35], s[64:65] offset:0
	global_store_dwordx4 v112, v[36:39], s[64:65] offset:1024
	global_store_dwordx4 v112, v[40:43], s[64:65] offset:2048
	global_store_dwordx4 v112, v[44:47], s[64:65] offset:3072
	s_add_u32 s23, s23, 4

; __device__ __forceinline__ unsigned pk2(float lo, float hi) { return (unsigned)f2bf(lo) | ((unsigned)f2bf(hi) << 16); }
; __device__ __forceinline__ void norm_phase(KP P, const float* g, const float* MODl, int shc, int scc, bool from_input, int npart) {
;     ...
;                 for (int j = 0; j < 4; ++j) ss[u] += v[u][j].x * v[u][j].x + v[u][j].y * v[u][j].y + v[u][j].z * v[u][j].z + v[u][j].w * v[u][j].w;
;                 if (from_input || (t >= SEQ && npart > 0)) {
; #pragma unroll
;                     for (int j = 0; j < 4; ++j) ((float4*)(H + (size_t)row * DM))[lane + 64 * j] = v[u][j]; }
;                 const float r = rsqrtf(wave_sum(ss[u]) * (1.f / DM) + 1e-6f);
;                 const float* sh = MODl + w * NMOD + shc * 1024; const float* sc = MODl + w * NMOD + scc * 1024;
; #pragma unroll
;                 for (int j = 0; j < 4; ++j) { const int c = (lane + 64 * j) * 4; const float4 gg = *(const float4*)(g + c), s4 = *(const float4*)(sh + c), c4 = *(const float4*)(sc + c);
;                     uint2 o; o.x = pk2(v[u][j].x * r * gg.x * (1.f + c4.x) + s4.x, v[u][j].y * r * gg.y * (1.f + c4.y) + s4.y);
;                     o.y = pk2(v[u][j].z * r * gg.z * (1.f + c4.z) + s4.z, v[u][j].w * r * gg.w * (1.f + c4.w) + s4.w);
;                     *(uint2*)(XN + (size_t)row * DM + c) = o; } } }
.Lnm_fi2_tabok:
	v_pk_mul_f32 v[120:121], v[32:33], v[32:33]
	v_add_f32_e32 v125, v121, v120
	v_pk_mul_f32 v[120:121], v[34:35], v[34:35]
	v_add_f32_e32 v125, v120, v125
	v_add_f32_e32 v125, v121, v125
	v_pk_mul_f32 v[120:121], v[36:37], v[36:37]
	v_add_f32_e32 v124, v121, v120
	v_pk_mul_f32 v[120:121], v[38:39], v[38:39]
	v_add_f32_e32 v124, v120, v124
	v_add_f32_e32 v124, v121, v124
	v_add_f32_e32 v125, v124, v125
	v_pk_mul_f32 v[120:121], v[40:41], v[40:41]
	v_add_f32_e32 v124, v121, v120
	v_pk_mul_f32 v[120:121], v[42:43], v[42:43]
	v_add_f32_e32 v124, v120, v124
	v_add_f32_e32 v124, v121, v124
	v_add_f32_e32 v125, v124, v125
	v_pk_mul_f32 v[120:121], v[44:45], v[44:45]
	v_add_f32_e32 v124, v121, v120
	v_pk_mul_f32 v[120:121], v[46:47], v[46:47]
	v_add_f32_e32 v124, v120, v124
	v_add_f32_e32 v124, v121, v124
	v_add_f32_e32 v125, v124, v125
	ds_bpermute_b32 v120, v114, v125
	s_waitcnt lgkmcnt(0)
	v_add_f32_e32 v125, v125, v120
	ds_bpermute_b32 v120, v115, v125
	s_waitcnt lgkmcnt(0)
	v_add_f32_e32 v125, v125, v120
	ds_bpermute_b32 v120, v116, v125
	s_waitcnt lgkmcnt(0)
	v_add_f32_e32 v125, v125, v120
	ds_bpermute_b32 v120, v117, v125
	s_waitcnt lgkmcnt(0)
	v_add_f32_e32 v125, v125, v120
	ds_bpermute_b32 v120, v118, v125
	s_waitcnt lgkmcnt(0)
	v_add_f32_e32 v125, v125, v120
	ds_bpermute_b32 v120, v119, v125
	s_waitcnt lgkmcnt(0)
	v_add_f32_e32 v125, v125, v120
	v_fmamk_f32 v125, v125, 0x3a800000, v217
	v_rsq_f32_e32 v122, v125
	s_lshl_b32 s31, s0, 11
	s_add_u32 s6, s62, s31
	s_addc_u32 s7, s63, 0
	v_pk_mul_f32 v[124:125], v[32:33], v[122:123] op_sel_hi:[1,0]
	v_pk_mul_f32 v[124:125], v[64:65], v[124:125]
	v_pk_fma_f32 v[124:125], v[96:97], v[124:125], v[80:81]
	v_pk_mul_f32 v[120:121], v[34:35], v[122:123] op_sel_hi:[1,0]
	v_pk_mul_f32 v[120:121], v[66:67], v[120:121]
	v_pk_fma_f32 v[120:121], v[98:99], v[120:121], v[82:83]
	v_cvt_pk_bf16_f32 v124, v124, v125
	v_cvt_pk_bf16_f32 v125, v120, v121
	global_store_dwordx2 v113, v[124:125], s[6:7] offset:0
	v_pk_mul_f32 v[124:125], v[36:37], v[122:123] op_sel_hi:[1,0]
	v_pk_mul_f32 v[124:125], v[68:69], v[124:125]
	v_pk_fma_f32 v[124:125], v[100:101], v[124:125], v[84:85]
	v_pk_mul_f32 v[120:121], v[38:39], v[122:123] op_sel_hi:[1,0]
	v_pk_mul_f32 v[120:121], v[70:71], v[120:121]
	v_pk_fma_f32 v[120:121], v[102:103], v[120:121], v[86:87]
	v_cvt_pk_bf16_f32 v124, v124, v125
	v_cvt_pk_bf16_f32 v125, v120, v121
	global_store_dwordx2 v113, v[124:125], s[6:7] offset:512
	v_pk_mul_f32 v[124:125], v[40:41], v[122:123] op_sel_hi:[1,0]
	v_pk_mul_f32 v[124:125], v[72:73], v[124:125]
	v_pk_fma_f32 v[124:125], v[104:105], v[124:125], v[88:89]
	v_pk_mul_f32 v[120:121], v[42:43], v[122:123] op_sel_hi:[1,0]
	v_pk_mul_f32 v[120:121], v[74:75], v[120:121]
	v_pk_fma_f32 v[120:121], v[106:107], v[120:121], v[90:91]
	v_cvt_pk_bf16_f32 v124, v124, v125
	v_cvt_pk_bf16_f32 v125, v120, v121
	global_store_dwordx2 v113, v[124:125], s[6:7] offset:1024
	v_pk_mul_f32 v[124:125], v[44:45], v[122:123] op_sel_hi:[1,0]
	v_pk_mul_f32 v[124:125], v[76:77], v[124:125]
	v_pk_fma_f32 v[124:125], v[108:109], v[124:125], v[92:93]
	v_pk_mul_f32 v[120:121], v[46:47], v[122:123] op_sel_hi:[1,0]
	v_pk_mul_f32 v[120:121], v[78:79], v[120:121]
	v_pk_fma_f32 v[120:121], v[110:111], v[120:121], v[94:95]
	v_cvt_pk_bf16_f32 v124, v124, v125
	v_cvt_pk_bf16_f32 v125, v120, v121
	global_store_dwordx2 v113, v[124:125], s[6:7] offset:1536
	s_add_u32 s23, s23, 4
	s_mul_i32 s31, s2, 4
	s_add_i32 s31, s0, s31
	s_cmp_lt_u32 s31, 0x4200
	s_cbranch_scc0 .Lnm_fi2_nopf
	s_cmp_ge_u32 s31, 0x2100
	s_cselect_b32 s6, 1, 0
	s_mul_i32 s7, s6, 0x2100
	s_sub_u32 s7, s31, s7
	s_cmp_ge_u32 s7, 0x2000
	s_cbranch_scc1 .Lnm_fi6_ctxp
	s_lshl_b32 s6, s6, 13
	s_add_u32 s6, s6, s7
	s_lshl_b32 s6, s6, 12
	s_add_u32 s64, s20, s6
	s_addc_u32 s65, s21, 0
	s_branch .Lnm_fi6_ptrd

; __device__ __forceinline__ void norm_phase(KP P, const float* g, const float* MODl, int shc, int scc, bool from_input, int npart) {
;     ...
;                 if (from_input || (t >= SEQ && npart > 0)) {
; #pragma unroll
;                     for (int j = 0; j < 4; ++j) ((float4*)(H + (size_t)row * DM))[lane + 64 * j] = v[u][j]; }
.Lnm_fi3_wdone:
	s_cmp_ge_u32 s0, 0x2100
	s_cselect_b32 s6, 1, 0
	s_mul_i32 s7, s6, 0x2100
	s_sub_u32 s7, s0, s7
	s_cmp_ge_u32 s7, 0x2000
	s_cselect_b32 s30, 2, s6
	s_lshl_b32 s31, s0, 12
	s_add_u32 s64, s60, s31
	s_addc_u32 s65, s61, 0
	s_cmp_lt_u32 s7, 0x2000
	s_cbranch_scc1 .Lnm_fi3_noh
	global_store_dwordx4 v112, v[48:51], s[64:65] offset:0
	global_store_dwordx4 v112, v[52:55], s[64:65] offset:1024
	global_store_dwordx4 v112, v[56:59], s[64:65] offset:2048
	global_store_dwordx4 v112, v[60:63], s[64:65] offset:3072
	s_add_u32 s23, s23, 4

; __device__ __forceinline__ unsigned pk2(float lo, float hi) { return (unsigned)f2bf(lo) | ((unsigned)f2bf(hi) << 16); }
; __device__ __forceinline__ void norm_phase(KP P, const float* g, const float* MODl, int shc, int scc, bool from_input, int npart) {
;     ...
;                 for (int j = 0; j < 4; ++j) ss[u] += v[u][j].x * v[u][j].x + v[u][j].y * v[u][j].y + v[u][j].z * v[u][j].z + v[u][j].w * v[u][j].w;
;                 if (from_input || (t >= SEQ && npart > 0)) {
; #pragma unroll
;                     for (int j = 0; j < 4; ++j) ((float4*)(H + (size_t)row * DM))[lane + 64 * j] = v[u][j]; }
;                 const float r = rsqrtf(wave_sum(ss[u]) * (1.f / DM) + 1e-6f);
;                 const float* sh = MODl + w * NMOD + shc * 1024; const float* sc = MODl + w * NMOD + scc * 1024;
; #pragma unroll
;                 for (int j = 0; j < 4; ++j) { const int c = (lane + 64 * j) * 4; const float4 gg = *(const float4*)(g + c), s4 = *(const float4*)(sh + c), c4 = *(const float4*)(sc + c);
;                     uint2 o; o.x = pk2(v[u][j].x * r * gg.x * (1.f + c4.x) + s4.x, v[u][j].y * r * gg.y * (1.f + c4.y) + s4.y);
;                     o.y = pk2(v[u][j].z * r * gg.z * (1.f + c4.z) + s4.z, v[u][j].w * r * gg.w * (1.f + c4.w) + s4.w);
;                     *(uint2*)(XN + (size_t)row * DM + c) = o; } } }
.Lnm_fi3_tabok:
	v_pk_mul_f32 v[120:121], v[48:49], v[48:49]
	v_add_f32_e32 v125, v121, v120
	v_pk_mul_f32 v[120:121], v[50:51], v[50:51]
	v_add_f32_e32 v125, v120, v125
	v_add_f32_e32 v125, v121, v125
	v_pk_mul_f32 v[120:121], v[52:53], v[52:53]
	v_add_f32_e32 v124, v121, v120
	v_pk_mul_f32 v[120:121], v[54:55], v[54:55]
	v_add_f32_e32 v124, v120, v124
	v_add_f32_e32 v124, v121, v124
	v_add_f32_e32 v125, v124, v125
	v_pk_mul_f32 v[120:121], v[56:57], v[56:57]
	v_add_f32_e32 v124, v121, v120
	v_pk_mul_f32 v[120:121], v[58:59], v[58:59]
	v_add_f32_e32 v124, v120, v124
	v_add_f32_e32 v124, v121, v124
	v_add_f32_e32 v125, v124, v125
	v_pk_mul_f32 v[120:121], v[60:61], v[60:61]
	v_add_f32_e32 v124, v121, v120
	v_pk_mul_f32 v[120:121], v[62:63], v[62:63]
	v_add_f32_e32 v124, v120, v124
	v_add_f32_e32 v124, v121, v124
	v_add_f32_e32 v125, v124, v125
	ds_bpermute_b32 v120, v114, v125
	s_waitcnt lgkmcnt(0)
	v_add_f32_e32 v125, v125, v120
	ds_bpermute_b32 v120, v115, v125
	s_waitcnt lgkmcnt(0)
	v_add_f32_e32 v125, v125, v120
	ds_bpermute_b32 v120, v116, v125
	s_waitcnt lgkmcnt(0)
	v_add_f32_e32 v125, v125, v120
	ds_bpermute_b32 v120, v117, v125
	s_waitcnt lgkmcnt(0)
	v_add_f32_e32 v125, v125, v120
	ds_bpermute_b32 v120, v118, v125
	s_waitcnt lgkmcnt(0)
	v_add_f32_e32 v125, v125, v120
	ds_bpermute_b32 v120, v119, v125
	s_waitcnt lgkmcnt(0)
	v_add_f32_e32 v125, v125, v120
	v_fmamk_f32 v125, v125, 0x3a800000, v217
	v_rsq_f32_e32 v122, v125
	s_lshl_b32 s31, s0, 11
	s_add_u32 s6, s62, s31
	s_addc_u32 s7, s63, 0
	v_pk_mul_f32 v[124:125], v[48:49], v[122:123] op_sel_hi:[1,0]
	v_pk_mul_f32 v[124:125], v[64:65], v[124:125]
	v_pk_fma_f32 v[124:125], v[96:97], v[124:125], v[80:81]
	v_pk_mul_f32 v[120:121], v[50:51], v[122:123] op_sel_hi:[1,0]
	v_pk_mul_f32 v[120:121], v[66:67], v[120:121]
	v_pk_fma_f32 v[120:121], v[98:99], v[120:121], v[82:83]
	v_cvt_pk_bf16_f32 v124, v124, v125
	v_cvt_pk_bf16_f32 v125, v120, v121
	global_store_dwordx2 v113, v[124:125], s[6:7] offset:0
	v_pk_mul_f32 v[124:125], v[52:53], v[122:123] op_sel_hi:[1,0]
	v_pk_mul_f32 v[124:125], v[68:69], v[124:125]
	v_pk_fma_f32 v[124:125], v[100:101], v[124:125], v[84:85]
	v_pk_mul_f32 v[120:121], v[54:55], v[122:123] op_sel_hi:[1,0]
	v_pk_mul_f32 v[120:121], v[70:71], v[120:121]
	v_pk_fma_f32 v[120:121], v[102:103], v[120:121], v[86:87]
	v_cvt_pk_bf16_f32 v124, v124, v125
	v_cvt_pk_bf16_f32 v125, v120, v121
	global_store_dwordx2 v113, v[124:125], s[6:7] offset:512
	v_pk_mul_f32 v[124:125], v[56:57], v[122:123] op_sel_hi:[1,0]
	v_pk_mul_f32 v[124:125], v[72:73], v[124:125]
	v_pk_fma_f32 v[124:125], v[104:105], v[124:125], v[88:89]
	v_pk_mul_f32 v[120:121], v[58:59], v[122:123] op_sel_hi:[1,0]
	v_pk_mul_f32 v[120:121], v[74:75], v[120:121]
	v_pk_fma_f32 v[120:121], v[106:107], v[120:121], v[90:91]
	v_cvt_pk_bf16_f32 v124, v124, v125
	v_cvt_pk_bf16_f32 v125, v120, v121
	global_store_dwordx2 v113, v[124:125], s[6:7] offset:1024
	v_pk_mul_f32 v[124:125], v[60:61], v[122:123] op_sel_hi:[1,0]
	v_pk_mul_f32 v[124:125], v[76:77], v[124:125]
	v_pk_fma_f32 v[124:125], v[108:109], v[124:125], v[92:93]
	v_pk_mul_f32 v[120:121], v[62:63], v[122:123] op_sel_hi:[1,0]
	v_pk_mul_f32 v[120:121], v[78:79], v[120:121]
	v_pk_fma_f32 v[120:121], v[110:111], v[120:121], v[94:95]
	v_cvt_pk_bf16_f32 v124, v124, v125
	v_cvt_pk_bf16_f32 v125, v120, v121
	global_store_dwordx2 v113, v[124:125], s[6:7] offset:1536
	s_add_u32 s23, s23, 4
	s_mul_i32 s31, s2, 4
	s_add_i32 s31, s0, s31
	s_cmp_lt_u32 s31, 0x4200
	s_cbranch_scc0 .Lnm_fi3_nopf
	s_cmp_ge_u32 s31, 0x2100
	s_cselect_b32 s6, 1, 0
	s_mul_i32 s7, s6, 0x2100
	s_sub_u32 s7, s31, s7
	s_cmp_ge_u32 s7, 0x2000
	s_cbranch_scc1 .Lnm_fi7_ctxp
	s_lshl_b32 s6, s6, 13
	s_add_u32 s6, s6, s7
	s_lshl_b32 s6, s6, 12
	s_add_u32 s64, s20, s6
	s_addc_u32 s65, s21, 0
	s_branch .Lnm_fi7_ptrd
